# hot hand-written loop heads (MLA bodies, sel blocks, top-16 search) aligned to 64 bytes
# speedup vs baseline: 1.0037x; 1.0029x over previous
; #define LAS __attribute__((address_space(3)))
; #define ATT_BAR() asm volatile("s_waitcnt lgkmcnt(0)\n\ts_barrier" ::: "memory")
; template <int DQK> __device__ __forceinline__ void x1_tile(LAS unsigned char* lds, const bf16x8 (&qf)[2][DQK / 32], const float (&m)[2], f32x4 (&s)[2][4], int fr, int fq) {
;     constexpr int NKS = DQK / 32;
; #pragma unroll
;     for (int q = 0; q < 2; ++q) { const float c = (m[q] > -1e29f) ? -m[q] : 0.f;
; #pragma unroll
;         for (int ss = 0; ss < 4; ++ss) s[q][ss] = (f32x4){c, c, c, c}; }
; #pragma unroll
;     for (int ss = 0; ss < 4; ++ss)
; #pragma unroll
;         for (int ks = 0; ks < NKS; ++ks) {
;             const bf16x8 kf = *(const LAS bf16x8*)(lds + k_off<DQK>(16 * ss + fr, 4 * ks + fq));
; #pragma unroll
;             for (int q = 0; q < 2; ++q) s[q][ss] = __builtin_amdgcn_mfma_f32_16x16x32_bf16(kf, qf[q][ks], s[q][ss], 0, 0, 0);
;         }
; }
; template <int DQK> __device__ __forceinline__ void causal_pass_pipe(LAS unsigned char* lds, const bf16* K0, int p0, const bf16* K1, int p1, const bf16* V, int pv, int thi,
;         const bf16x8 (&qf)[2][DQK / 32], const int (&tpos)[2], int wave_tmin, int wave_tmax, f32x4 (&o)[2][4], int tid) {
;     ...
;     float m[2] = {NEG, NEG}, l[2] = {0.f, 0.f};
; #pragma unroll
;     for (int i = 0; i < 2; ++i)
; #pragma unroll
;         for (int dt = 0; dt < 4; ++dt) o[i][dt] = (f32x4){0.f, 0.f, 0.f, 0.f};
;     Stage<DQK> st;
;     {
;         Stage<DQK> st1;
;         stage_load<DQK>(st, K0, p0, K1, p1, V, pv, 0, true, tid);
;         if (thi >= 1) stage_load<DQK>(st1, K0, p0, K1, p1, V, pv, 1, true, tid);
;         stage_store<DQK>(st, lds, true, tid);
;         if (thi >= 1) stage_store<DQK>(st1, lds + SLOT, true, tid);
;     }
;     ATT_BAR();
;     f32x4 sa[2][4], sb[2][4]; bool ca = true, cb = false;
;     x1_tile<DQK>(lds, qf, m, sa, fr, fq);
;     if (63 <= wave_tmin) x2_tile<true>(0, tpos, m, l, o, sa, fq); else x2_tile<false>(0, tpos, m, l, o, sa, fq);
.Lmla_nok1_0:
	v_mov_b32_e32 v96, 0
	v_mov_b32_e32 v97, 0
	v_mov_b32_e32 v98, 0
	v_mov_b32_e32 v99, 0
	v_mov_b32_e32 v88, 0
	v_mov_b32_e32 v89, 0
	v_mov_b32_e32 v90, 0
	v_mov_b32_e32 v91, 0
	v_mov_b32_e32 v92, 0
	v_mov_b32_e32 v93, 0
	v_mov_b32_e32 v94, 0
	v_mov_b32_e32 v95, 0
	v_mov_b32_e32 v48, 0
	v_mov_b32_e32 v49, 0
	v_mov_b32_e32 v50, 0
	v_mov_b32_e32 v51, 0
	v_mov_b32_e32 v165, 0
	v_mov_b32_e32 v200, v183
	v_mov_b32_e32 v84, 0
	v_mov_b32_e32 v85, 0
	v_mov_b32_e32 v86, 0
	v_mov_b32_e32 v87, 0
	v_mov_b32_e32 v76, 0
	v_mov_b32_e32 v77, 0
	v_mov_b32_e32 v78, 0
	v_mov_b32_e32 v79, 0
	v_mov_b32_e32 v80, 0
	v_mov_b32_e32 v81, 0
	v_mov_b32_e32 v82, 0
	v_mov_b32_e32 v83, 0
	v_mov_b32_e32 v56, 0
	v_mov_b32_e32 v57, 0
	v_mov_b32_e32 v58, 0
	v_mov_b32_e32 v59, 0
	v_mov_b32_e32 v164, 0
	v_mov_b32_e32 v211, v183
	s_mov_b32 s100, 0x20000
	s_mov_b32 s101, 0
	v_cmp_lt_f32_e64 s[66:67], s77, v200
	v_cmp_lt_f32_e64 s[68:69], s77, v211
	s_nop 1
	v_cndmask_b32_e64 v197, 0, v200, s[66:67]
	v_cndmask_b32_e64 v198, 0, v211, s[68:69]
	s_and_b64 s[64:65], s[66:67], s[68:69]
	v_sub_f32_e32 v204, 0, v197
	v_mov_b32_e32 v205, v204
	v_mov_b32_e32 v206, v204
	v_mov_b32_e32 v207, v204
	v_sub_f32_e32 v252, 0, v198
	v_mov_b32_e32 v253, v252
	v_mov_b32_e32 v254, v252
	v_mov_b32_e32 v255, v252
	ds_read_b128 v[236:239], v199
	ds_read_b128 v[240:243], v201
	ds_read_b128 v[244:247], v210
	s_waitcnt lgkmcnt(0)
	v_mfma_f32_16x16x32_bf16 v[100:103], v[236:239], v[0:3], v[204:207]
	v_mfma_f32_16x16x32_bf16 v[116:119], v[236:239], v[12:15], v[252:255]
	v_mfma_f32_16x16x32_bf16 v[100:103], v[240:243], v[4:7], v[100:103]
	v_mfma_f32_16x16x32_bf16 v[116:119], v[240:243], v[16:19], v[116:119]
	v_mfma_f32_16x16x32_bf16 v[100:103], v[244:247], v[8:11], v[100:103]
	v_mfma_f32_16x16x32_bf16 v[116:119], v[244:247], v[20:23], v[116:119]
	ds_read_b128 v[236:239], v199 offset:4096
	ds_read_b128 v[240:243], v201 offset:4096
	ds_read_b128 v[244:247], v210 offset:4096
	s_waitcnt lgkmcnt(0)
	v_mfma_f32_16x16x32_bf16 v[104:107], v[236:239], v[0:3], v[204:207]
	v_mfma_f32_16x16x32_bf16 v[120:123], v[236:239], v[12:15], v[252:255]
	v_mfma_f32_16x16x32_bf16 v[104:107], v[240:243], v[4:7], v[104:107]
	v_mfma_f32_16x16x32_bf16 v[120:123], v[240:243], v[16:19], v[120:123]
	v_mfma_f32_16x16x32_bf16 v[104:107], v[244:247], v[8:11], v[104:107]
	v_mfma_f32_16x16x32_bf16 v[120:123], v[244:247], v[20:23], v[120:123]
	ds_read_b128 v[236:239], v199 offset:8192
	ds_read_b128 v[240:243], v201 offset:8192
	ds_read_b128 v[244:247], v210 offset:8192
	s_waitcnt lgkmcnt(0)
	v_mfma_f32_16x16x32_bf16 v[108:111], v[236:239], v[0:3], v[204:207]
	v_mfma_f32_16x16x32_bf16 v[124:127], v[236:239], v[12:15], v[252:255]
	v_mfma_f32_16x16x32_bf16 v[108:111], v[240:243], v[4:7], v[108:111]
	v_mfma_f32_16x16x32_bf16 v[124:127], v[240:243], v[16:19], v[124:127]
	v_mfma_f32_16x16x32_bf16 v[108:111], v[244:247], v[8:11], v[108:111]
	v_mfma_f32_16x16x32_bf16 v[124:127], v[244:247], v[20:23], v[124:127]
	ds_read_b128 v[236:239], v199 offset:12288
	ds_read_b128 v[240:243], v201 offset:12288
	ds_read_b128 v[244:247], v210 offset:12288
	s_waitcnt lgkmcnt(0)
	v_mfma_f32_16x16x32_bf16 v[112:115], v[236:239], v[0:3], v[204:207]
	v_mfma_f32_16x16x32_bf16 v[128:131], v[236:239], v[12:15], v[252:255]
	v_mfma_f32_16x16x32_bf16 v[112:115], v[240:243], v[4:7], v[112:115]
	v_mfma_f32_16x16x32_bf16 v[128:131], v[240:243], v[16:19], v[128:131]
	v_mfma_f32_16x16x32_bf16 v[112:115], v[244:247], v[8:11], v[112:115]
	v_mfma_f32_16x16x32_bf16 v[128:131], v[244:247], v[20:23], v[128:131]
	s_nop 7
	s_nop 7
	s_add_i32 s32, s49, 1
	s_cmp_eq_u32 s32, s9
	s_cbranch_scc1 .Lmla_mask5
	s_branch .Lmla_slow5_0
	.p2align 6

; template <int DQK> __device__ __forceinline__ void causal_pass_pipe(LAS unsigned char* lds, const bf16* K0, int p0, const bf16* K1, int p1, const bf16* V, int pv, int thi,
;         const bf16x8 (&qf)[2][DQK / 32], const int (&tpos)[2], int wave_tmin, int wave_tmax, f32x4 (&o)[2][4], int tid) {
;     ...
;     for (int t = 0; t <= thi; t += 2) {
;         PIPE_STEP(sa, sb, ca, cb, t);
;         if (t + 1 <= thi) PIPE_STEP(sb, sa, cb, ca, t + 1);
;     }
.Lmla_bar0:
	s_waitcnt lgkmcnt(0)
	s_barrier
	s_add_i32 s49, s49, 1
	s_cmp_le_u32 s49, s8
	s_cbranch_scc1 .Lmla_it1
	s_branch .Lmla_exit
	.p2align 6

; #define LAS __attribute__((address_space(3)))
; __device__ __forceinline__ void nsa_item(LAS unsigned char* lds, const NsaPtrs& P, int b, int g, int qb, int tid) {
;     ...
;         int tid_k = tid; asm volatile("" : "+v"(tid_k)); const int tk = tid_k >> 3, part = tid_k & 7;
;         unsigned v[16]; int cnt[16];
;         LAS unsigned* impu = (LAS unsigned*)imp;
; #pragma unroll
;         for (int jj = 0; jj < 16; ++jj) { const int j = part * 16 + jj; const bool forced = (j == 0) || (j == qb) || (j == qb - 1);
;             const unsigned key = forced ? 0x7fffff80u : (__float_as_uint(fmaxf(imp[tk * ISTR + j], 0.f)) & 0xffffff80u); v[jj] = key | (unsigned)(127 - j); cnt[jj] = 0; }
;         __syncthreads();
; #pragma unroll
;         for (int jj = 0; jj < 16; ++jj) impu[tk * ISTR + part * 16 + jj] = v[jj];
;         __syncthreads();
;         for (int k = 0; k <= qb; ++k) { const unsigned vk = impu[tk * ISTR + k];
; #pragma unroll
;             for (int jj = 0; jj < 16; ++jj) cnt[jj] += (vk > v[jj]) ? 1 : 0; }
;         unsigned bits = 0u;
; #pragma unroll
;         for (int jj = 0; jj < 16; ++jj) { const int j = part * 16 + jj; if (j <= qb && cnt[jj] < 16) bits |= (1u << jj); }
;         ((LAS unsigned short*)(lds + OFF_SEL))[tk * 8 + part] = (unsigned short)bits;
.LBB0_1071:
	s_or_b64 exec, exec, s[6:7]
	v_sub_u32_e32 v0, v2, v47
	v_sub_u32_e32 v12, v12, v37
	v_sub_u32_e32 v3, v3, v33
	v_add_u32_e32 v2, 0x7f, v0
	v_sub_u32_e32 v0, v16, v46
	v_sub_u32_e32 v15, v15, v44
	v_sub_u32_e32 v14, v14, v41
	v_sub_u32_e32 v13, v13, v39
	v_add_u32_e32 v24, 0x7f, v12
	v_sub_u32_e32 v11, v11, v35
	v_sub_u32_e32 v5, v5, v7
	v_add_u32_e32 v12, 0x7f, v3
	v_sub_u32_e32 v3, v19, v48
	s_add_i32 s10, s72, 1
	v_add_u32_e32 v16, 0x7f, v0
	v_sub_u32_e32 v0, v17, v45
	v_add_u32_e32 v18, 0x7f, v15
	v_sub_u32_e32 v6, v6, v42
	v_add_u32_e32 v20, 0x7f, v14
	v_sub_u32_e32 v4, v4, v40
	v_add_u32_e32 v22, 0x7f, v13
	v_sub_u32_e32 v10, v10, v38
	v_sub_u32_e32 v8, v8, v36
	v_add_u32_e32 v26, 0x7f, v11
	v_sub_u32_e32 v9, v9, v34
	v_add_u32_e32 v28, 0x7f, v5
	v_add_u32_e32 v30, 0x7f, v3
	s_cmp_lg_u32 s72, 0
	v_add_u32_e32 v0, 0x7f, v0
	v_add_u32_e32 v6, 0x7f, v6
	v_add_u32_e32 v4, 0x7f, v4
	v_add_u32_e32 v10, 0x7f, v10
	v_add_u32_e32 v8, 0x7f, v8
	v_add_u32_e32 v14, 0x7f, v9
	v_lshl_add_u32 v17, v1, 6, v49
	v_mov_b32_e32 v13, v28
	v_mov_b32_e32 v15, v26
	v_mov_b32_e32 v9, v24
	v_mov_b32_e32 v11, v22
	v_mov_b32_e32 v5, v20
	v_mov_b32_e32 v7, v18
	v_mov_b32_e32 v1, v16
	v_mov_b32_e32 v3, v30
	s_cselect_b64 s[8:9], -1, 0
	s_cmp_eq_u32 s72, 0
	s_mov_b32 s11, 0
	v_mov_b32_e32 v51, 0
	s_cmp_lt_u32 s72, 16
	s_cbranch_scc1 .Ltopk_sel
	v_sub_u32_e32 v50, s72, v33
	v_cmp_le_i32_e64 s[12:13], 0, v50
	v_cmp_le_i32_e64 s[14:15], 1, v50
	v_cmp_le_i32_e64 s[20:21], 2, v50
	v_cndmask_b32_e64 v12, 0, v12, s[12:13]
	v_cmp_le_i32_e64 s[12:13], 3, v50
	v_cndmask_b32_e64 v28, 0, v28, s[14:15]
	v_cmp_le_i32_e64 s[14:15], 4, v50
	v_cndmask_b32_e64 v14, 0, v14, s[20:21]
	v_cmp_le_i32_e64 s[20:21], 5, v50
	v_cndmask_b32_e64 v26, 0, v26, s[12:13]
	v_cmp_le_i32_e64 s[12:13], 6, v50
	v_cndmask_b32_e64 v8, 0, v8, s[14:15]
	v_cmp_le_i32_e64 s[14:15], 7, v50
	v_cndmask_b32_e64 v24, 0, v24, s[20:21]
	v_cmp_le_i32_e64 s[20:21], 8, v50
	v_cndmask_b32_e64 v10, 0, v10, s[12:13]
	v_cmp_le_i32_e64 s[12:13], 9, v50
	v_cndmask_b32_e64 v22, 0, v22, s[14:15]
	v_cmp_le_i32_e64 s[14:15], 10, v50
	v_cndmask_b32_e64 v4, 0, v4, s[20:21]
	v_cmp_le_i32_e64 s[20:21], 11, v50
	v_cndmask_b32_e64 v20, 0, v20, s[12:13]
	v_cmp_le_i32_e64 s[12:13], 12, v50
	v_cndmask_b32_e64 v6, 0, v6, s[14:15]
	v_cmp_le_i32_e64 s[14:15], 13, v50
	v_cndmask_b32_e64 v18, 0, v18, s[20:21]
	v_cmp_le_i32_e64 s[20:21], 14, v50
	v_cndmask_b32_e64 v0, 0, v0, s[12:13]
	v_cmp_le_i32_e64 s[12:13], 15, v50
	s_nop 1
	v_cndmask_b32_e64 v16, 0, v16, s[14:15]
	v_cndmask_b32_e64 v2, 0, v2, s[20:21]
	v_cndmask_b32_e64 v30, 0, v30, s[12:13]
	v_bfrev_b32_e32 v54, -2
	s_mov_b32 s6, 0x40000000
	.p2align 6

; #define LAS __attribute__((address_space(3)))
; __device__ __forceinline__ void sel_pass(LAS unsigned char* lds, const bf16* K0, const bf16* V, int thi, const bf16x8 (&qf)[2][2], const int (&tpos)[2], const int (&tok)[2], int wave_tmin, int wave_tmax,
;         f32x4 (&o)[2][4], float (&mfin)[2], float (&linv)[2], int tid, int fr, int fq) {
;     ...
;         for (int u = 0; u < 2; ++u) {
;             const int t = 2 * g + u;
;             if (t > thi) continue;
;             LAS unsigned char* buf = lds + (2 * par + u) * SEL_SLOT;
;             const int kbase = 64 * t;
;             if (kbase > wave_tmax) continue;
;             const bool full = kbase + 63 <= wave_tmin;
;             bool rowsel[2];
; #pragma unroll
;             for (int i = 0; i < 2; ++i) { const unsigned w = ((const LAS unsigned*)(lds + OFF_SEL))[tok[i] * 4 + (t >> 5)]; rowsel[i] = ((w >> (t & 31)) & 1u) != 0u; }
;             const bool n0 = __any(rowsel[0] ? 1 : 0) != 0, n1 = __any(rowsel[1] ? 1 : 0) != 0;
;             if (n0 && n1) { if (full) tile_x<64, SEL, true, 0, 2>(buf, qf, kbase, tpos, rowsel, m, l, o, s, fr, fq); else tile_x<64, SEL, false, 0, 2>(buf, qf, kbase, tpos, rowsel, m, l, o, s, fr, fq);
;                             tile_y<0, 2, SEL_V>(buf, l, o, s, fr, fq); }
;             else if (n0) { if (full) tile_x<64, SEL, true, 0, 1>(buf, qf, kbase, tpos, rowsel, m, l, o, s, fr, fq); else tile_x<64, SEL, false, 0, 1>(buf, qf, kbase, tpos, rowsel, m, l, o, s, fr, fq);
;                            tile_y<0, 1, SEL_V>(buf, l, o, s, fr, fq); }
;             else if (n1) { if (full) tile_x<64, SEL, true, 1, 1>(buf, qf, kbase, tpos, rowsel, m, l, o, s, fr, fq); else tile_x<64, SEL, false, 1, 1>(buf, qf, kbase, tpos, rowsel, m, l, o, s, fr, fq);
;                            tile_y<1, 1, SEL_V>(buf, l, o, s, fr, fq); }
;         }
.Lsel_done:
	s_branch .LBB0_1089
	.p2align 6

; template <int MODE> __device__ __forceinline__ bool key_ok(int kpos, int tpos, bool rowsel) {
;     if (MODE == CAUSAL) return kpos <= tpos;
;     if (MODE == WINDOW) return kpos <= tpos && kpos + 512 > tpos;
;     if (MODE == CMP) return 16 * kpos + 31 <= tpos;
;     return rowsel && kpos <= tpos;
; }
; template <int DQK, int MODE, bool FULL, int I0, int NQ> __device__ __forceinline__ void tile_x(LAS unsigned char* lds, const bf16x8 (&qf)[2][DQK / 32], int kbase, const int (&tpos)[2], const bool (&rowsel)[2],
;         float (&m)[2], float (&l)[2], f32x4 (&o)[2][4], f32x4 (&s)[2][4], int fr, int fq) {
;     ...
;                 for (int ss = 0; ss < 4; ++ss)
; #pragma unroll
;                     for (int i = 0; i < 4; ++i) { const bool ok = key_ok<MODE>(kbase + 16 * ss + 4 * fq + i, tpos[I0 + q], rowsel[I0 + q]); const float v = ok ? sq[ss][i] : NEG; sq[ss][i] = v; mx = fmaxf(mx, v); }
.Lsel_maskA:
	v_add_u32_e32 v254, s94, v142
	v_sub_u32_e32 v255, v116, v254
	v_cmp_le_i32_e64 s[100:101], 0, v255
	v_cmp_le_i32_e64 s[20:21], 1, v255
	v_cmp_le_i32_e64 s[64:65], 2, v255
	v_cndmask_b32_e64 v212, v183, v212, s[100:101]
	v_cmp_le_i32_e64 s[100:101], 3, v255
	v_cndmask_b32_e64 v213, v183, v213, s[20:21]
	v_cmp_le_i32_e64 s[20:21], 16, v255
	v_cndmask_b32_e64 v214, v183, v214, s[64:65]
	v_cmp_le_i32_e64 s[64:65], 17, v255
	v_cndmask_b32_e64 v215, v183, v215, s[100:101]
	v_cmp_le_i32_e64 s[100:101], 18, v255
	v_cndmask_b32_e64 v216, v183, v216, s[20:21]
	v_cmp_le_i32_e64 s[20:21], 19, v255
	v_cndmask_b32_e64 v217, v183, v217, s[64:65]
	v_cmp_le_i32_e64 s[64:65], 32, v255
	v_cndmask_b32_e64 v218, v183, v218, s[100:101]
	v_cmp_le_i32_e64 s[100:101], 33, v255
	v_cndmask_b32_e64 v219, v183, v219, s[20:21]
	v_cmp_le_i32_e64 s[20:21], 34, v255
	v_cndmask_b32_e64 v220, v183, v220, s[64:65]
	v_cmp_le_i32_e64 s[64:65], 35, v255
	v_cndmask_b32_e64 v221, v183, v221, s[100:101]
	v_cmp_le_i32_e64 s[100:101], 48, v255
	v_cndmask_b32_e64 v222, v183, v222, s[20:21]
	v_cmp_le_i32_e64 s[20:21], 49, v255
	v_cndmask_b32_e64 v223, v183, v223, s[64:65]
	v_cmp_le_i32_e64 s[64:65], 50, v255
	v_cndmask_b32_e64 v224, v183, v224, s[100:101]
	v_cmp_le_i32_e64 s[100:101], 51, v255
	s_nop 1
	v_cndmask_b32_e64 v225, v183, v225, s[20:21]
	v_cndmask_b32_e64 v226, v183, v226, s[64:65]
	v_cndmask_b32_e64 v227, v183, v227, s[100:101]
	s_branch .Lsel_slowA
	.p2align 6

; template <int MODE> __device__ __forceinline__ bool key_ok(int kpos, int tpos, bool rowsel) {
;     if (MODE == CAUSAL) return kpos <= tpos;
;     if (MODE == WINDOW) return kpos <= tpos && kpos + 512 > tpos;
;     if (MODE == CMP) return 16 * kpos + 31 <= tpos;
;     return rowsel && kpos <= tpos;
; }
; template <int DQK, int MODE, bool FULL, int I0, int NQ> __device__ __forceinline__ void tile_x(LAS unsigned char* lds, const bf16x8 (&qf)[2][DQK / 32], int kbase, const int (&tpos)[2], const bool (&rowsel)[2],
;         float (&m)[2], float (&l)[2], f32x4 (&o)[2][4], f32x4 (&s)[2][4], int fr, int fq) {
;     ...
;                 for (int ss = 0; ss < 4; ++ss)
; #pragma unroll
;                     for (int i = 0; i < 4; ++i) { const bool ok = key_ok<MODE>(kbase + 16 * ss + 4 * fq + i, tpos[I0 + q], rowsel[I0 + q]); const float v = ok ? sq[ss][i] : NEG; sq[ss][i] = v; mx = fmaxf(mx, v); }
.Lsel_maskB:
	v_add_u32_e32 v254, s94, v142
	v_sub_u32_e32 v255, v114, v254
	v_cmp_le_i32_e64 s[100:101], 0, v255
	v_cmp_le_i32_e64 s[20:21], 1, v255
	v_cmp_le_i32_e64 s[64:65], 2, v255
	v_cndmask_b32_e64 v212, v183, v212, s[100:101]
	v_cmp_le_i32_e64 s[100:101], 3, v255
	v_cndmask_b32_e64 v213, v183, v213, s[20:21]
	v_cmp_le_i32_e64 s[20:21], 16, v255
	v_cndmask_b32_e64 v214, v183, v214, s[64:65]
	v_cmp_le_i32_e64 s[64:65], 17, v255
	v_cndmask_b32_e64 v215, v183, v215, s[100:101]
	v_cmp_le_i32_e64 s[100:101], 18, v255
	v_cndmask_b32_e64 v216, v183, v216, s[20:21]
	v_cmp_le_i32_e64 s[20:21], 19, v255
	v_cndmask_b32_e64 v217, v183, v217, s[64:65]
	v_cmp_le_i32_e64 s[64:65], 32, v255
	v_cndmask_b32_e64 v218, v183, v218, s[100:101]
	v_cmp_le_i32_e64 s[100:101], 33, v255
	v_cndmask_b32_e64 v219, v183, v219, s[20:21]
	v_cmp_le_i32_e64 s[20:21], 34, v255
	v_cndmask_b32_e64 v220, v183, v220, s[64:65]
	v_cmp_le_i32_e64 s[64:65], 35, v255
	v_cndmask_b32_e64 v221, v183, v221, s[100:101]
	v_cmp_le_i32_e64 s[100:101], 48, v255
	v_cndmask_b32_e64 v222, v183, v222, s[20:21]
	v_cmp_le_i32_e64 s[20:21], 49, v255
	v_cndmask_b32_e64 v223, v183, v223, s[64:65]
	v_cmp_le_i32_e64 s[64:65], 50, v255
	v_cndmask_b32_e64 v224, v183, v224, s[100:101]
	v_cmp_le_i32_e64 s[100:101], 51, v255
	s_nop 1
	v_cndmask_b32_e64 v225, v183, v225, s[20:21]
	v_cndmask_b32_e64 v226, v183, v226, s[64:65]
	v_cndmask_b32_e64 v227, v183, v227, s[100:101]
	s_branch .Lsel_slowB
	.p2align 6
